# conv LayerNorm wave sums: DPP adds (hops 1-8) and v_permlane16/32_swap (hops 16,32) instead of six ds_bpermute round trips per reduction
# speedup vs baseline: 1.0072x; 1.0046x over previous
.LBB0_696:
	v_or_b32_e32 v47, s2, v91
	v_cndmask_b32_e64 v46, 0, 1, s[10:11]
	v_lshl_add_u32 v103, v47, 10, v92
	v_cmp_ne_u32_e32 vcc, 1, v46
	ds_read2st64_b32 v[46:47], v103 offset1:4
	ds_read2st64_b32 v[48:49], v103 offset0:8 offset1:12
	ds_read2st64_b32 v[50:51], v103 offset0:16 offset1:20
	ds_read2st64_b32 v[52:53], v103 offset0:24 offset1:28
	ds_read2st64_b32 v[104:105], v103 offset0:32 offset1:36
	ds_read2st64_b32 v[106:107], v103 offset0:40 offset1:44
	ds_read2st64_b32 v[108:109], v103 offset0:48 offset1:52
	ds_read2st64_b32 v[110:111], v103 offset0:56 offset1:60
	ds_read2st64_b32 v[112:113], v103 offset0:64 offset1:68
	ds_read2st64_b32 v[114:115], v103 offset0:72 offset1:76
	ds_read2st64_b32 v[116:117], v103 offset0:80 offset1:84
	ds_read2st64_b32 v[118:119], v103 offset0:88 offset1:92
	ds_read2st64_b32 v[120:121], v103 offset0:96 offset1:100
	ds_read2st64_b32 v[122:123], v103 offset0:104 offset1:108
	ds_read2st64_b32 v[124:125], v103 offset0:112 offset1:116
	ds_read2st64_b32 v[126:127], v103 offset0:120 offset1:124
	ds_read2st64_b32 v[128:129], v103 offset0:128 offset1:132
	ds_read2st64_b32 v[130:131], v103 offset0:136 offset1:140
	ds_read2st64_b32 v[132:133], v103 offset0:144 offset1:148
	s_waitcnt lgkmcnt(14)
	v_fma_f32 v46, v59, v46, v90
	v_fma_f32 v140, v59, v47, v90
	v_fma_f32 v141, v59, v48, v90
	v_fma_f32 v142, v59, v49, v90
	v_fma_f32 v143, v59, v50, v90
	v_fma_f32 v144, v59, v51, v90
	v_fma_f32 v145, v59, v52, v90
	v_fma_f32 v146, v59, v53, v90
	v_fmac_f32_e32 v46, v60, v47
	v_fmac_f32_e32 v140, v60, v48
	v_fmac_f32_e32 v141, v60, v49
	v_fmac_f32_e32 v142, v60, v50
	v_fmac_f32_e32 v143, v60, v51
	v_fmac_f32_e32 v144, v60, v52
	v_fmac_f32_e32 v145, v60, v53
	v_fmac_f32_e32 v146, v60, v104
	v_fmac_f32_e32 v46, v61, v48
	v_fmac_f32_e32 v140, v61, v49
	v_fmac_f32_e32 v141, v61, v50
	v_fmac_f32_e32 v142, v61, v51
	v_fmac_f32_e32 v143, v61, v52
	v_fmac_f32_e32 v144, v61, v53
	v_fmac_f32_e32 v145, v61, v104
	v_fmac_f32_e32 v146, v61, v105
	v_fmac_f32_e32 v46, v62, v49
	v_fmac_f32_e32 v140, v62, v50
	v_fmac_f32_e32 v141, v62, v51
	v_fmac_f32_e32 v142, v62, v52
	v_fmac_f32_e32 v143, v62, v53
	v_fmac_f32_e32 v144, v62, v104
	v_fmac_f32_e32 v145, v62, v105
	s_waitcnt lgkmcnt(13)
	v_fmac_f32_e32 v146, v62, v106
	v_fmac_f32_e32 v46, v63, v50
	v_fmac_f32_e32 v140, v63, v51
	v_fmac_f32_e32 v141, v63, v52
	v_fmac_f32_e32 v142, v63, v53
	v_fmac_f32_e32 v143, v63, v104
	v_fmac_f32_e32 v144, v63, v105
	v_fmac_f32_e32 v145, v63, v106
	v_fmac_f32_e32 v146, v63, v107
	v_fmac_f32_e32 v46, v64, v51
	v_fmac_f32_e32 v140, v64, v52
	v_fmac_f32_e32 v141, v64, v53
	v_fmac_f32_e32 v142, v64, v104
	v_fmac_f32_e32 v143, v64, v105
	v_fmac_f32_e32 v144, v64, v106
	v_fmac_f32_e32 v145, v64, v107
	s_waitcnt lgkmcnt(12)
	v_fmac_f32_e32 v146, v64, v108
	v_fmac_f32_e32 v46, v65, v52
	v_fmac_f32_e32 v140, v65, v53
	v_fmac_f32_e32 v141, v65, v104
	v_fmac_f32_e32 v142, v65, v105
	v_fmac_f32_e32 v143, v65, v106
	v_fmac_f32_e32 v144, v65, v107
	v_fmac_f32_e32 v145, v65, v108
	v_fmac_f32_e32 v146, v65, v109
	v_fmac_f32_e32 v46, v66, v53
	v_fmac_f32_e32 v140, v66, v104
	v_fmac_f32_e32 v141, v66, v105
	v_fmac_f32_e32 v142, v66, v106
	v_fmac_f32_e32 v143, v66, v107
	v_fmac_f32_e32 v144, v66, v108
	v_fmac_f32_e32 v145, v66, v109
	s_waitcnt lgkmcnt(11)
	v_fmac_f32_e32 v146, v66, v110
	v_fmac_f32_e32 v46, v67, v104
	v_fmac_f32_e32 v140, v67, v105
	v_fmac_f32_e32 v141, v67, v106
	v_fmac_f32_e32 v142, v67, v107
	v_fmac_f32_e32 v143, v67, v108
	v_fmac_f32_e32 v144, v67, v109
	v_fmac_f32_e32 v145, v67, v110
	v_fmac_f32_e32 v146, v67, v111
	v_fmac_f32_e32 v46, v68, v105
	v_fmac_f32_e32 v140, v68, v106
	v_fmac_f32_e32 v141, v68, v107
	v_fmac_f32_e32 v142, v68, v108
	v_fmac_f32_e32 v143, v68, v109
	v_fmac_f32_e32 v144, v68, v110
	v_fmac_f32_e32 v145, v68, v111
	s_waitcnt lgkmcnt(10)
	v_fmac_f32_e32 v146, v68, v112
	v_fmac_f32_e32 v46, v69, v106
	v_fmac_f32_e32 v140, v69, v107
	v_fmac_f32_e32 v141, v69, v108
	v_fmac_f32_e32 v142, v69, v109
	v_fmac_f32_e32 v143, v69, v110
	v_fmac_f32_e32 v144, v69, v111
	v_fmac_f32_e32 v145, v69, v112
	v_fmac_f32_e32 v146, v69, v113
	v_fmac_f32_e32 v46, v70, v107
	v_fmac_f32_e32 v140, v70, v108
	v_fmac_f32_e32 v141, v70, v109
	v_fmac_f32_e32 v142, v70, v110
	v_fmac_f32_e32 v143, v70, v111
	v_fmac_f32_e32 v144, v70, v112
	v_fmac_f32_e32 v145, v70, v113
	s_waitcnt lgkmcnt(9)
	v_fmac_f32_e32 v146, v70, v114
	v_fmac_f32_e32 v46, v71, v108
	v_fmac_f32_e32 v140, v71, v109
	v_fmac_f32_e32 v141, v71, v110
	v_fmac_f32_e32 v142, v71, v111
	v_fmac_f32_e32 v143, v71, v112
	v_fmac_f32_e32 v144, v71, v113
	v_fmac_f32_e32 v145, v71, v114
	v_fmac_f32_e32 v146, v71, v115
	v_fmac_f32_e32 v46, v72, v109
	v_fmac_f32_e32 v140, v72, v110
	v_fmac_f32_e32 v141, v72, v111
	v_fmac_f32_e32 v142, v72, v112
	v_fmac_f32_e32 v143, v72, v113
	v_fmac_f32_e32 v144, v72, v114
	v_fmac_f32_e32 v145, v72, v115
	s_waitcnt lgkmcnt(8)
	v_fmac_f32_e32 v146, v72, v116
	v_fmac_f32_e32 v46, v73, v110
	v_fmac_f32_e32 v140, v73, v111
	v_fmac_f32_e32 v141, v73, v112
	v_fmac_f32_e32 v142, v73, v113
	v_fmac_f32_e32 v143, v73, v114
	v_fmac_f32_e32 v144, v73, v115
	v_fmac_f32_e32 v145, v73, v116
	v_fmac_f32_e32 v146, v73, v117
	v_fmac_f32_e32 v46, v74, v111
	v_fmac_f32_e32 v140, v74, v112
	v_fmac_f32_e32 v141, v74, v113
	v_fmac_f32_e32 v142, v74, v114
	v_fmac_f32_e32 v143, v74, v115
	v_fmac_f32_e32 v144, v74, v116
	v_fmac_f32_e32 v145, v74, v117
	s_waitcnt lgkmcnt(7)
	v_fmac_f32_e32 v146, v74, v118
	v_fmac_f32_e32 v46, v75, v112
	v_fmac_f32_e32 v140, v75, v113
	v_fmac_f32_e32 v141, v75, v114
	v_fmac_f32_e32 v142, v75, v115
	v_fmac_f32_e32 v143, v75, v116
	v_fmac_f32_e32 v144, v75, v117
	v_fmac_f32_e32 v145, v75, v118
	v_fmac_f32_e32 v146, v75, v119
	v_fmac_f32_e32 v46, v76, v113
	v_fmac_f32_e32 v140, v76, v114
	v_fmac_f32_e32 v141, v76, v115
	v_fmac_f32_e32 v142, v76, v116
	v_fmac_f32_e32 v143, v76, v117
	v_fmac_f32_e32 v144, v76, v118
	v_fmac_f32_e32 v145, v76, v119
	s_waitcnt lgkmcnt(6)
	v_fmac_f32_e32 v146, v76, v120
	v_fmac_f32_e32 v46, v77, v114
	v_fmac_f32_e32 v140, v77, v115
	v_fmac_f32_e32 v141, v77, v116
	v_fmac_f32_e32 v142, v77, v117
	v_fmac_f32_e32 v143, v77, v118
	v_fmac_f32_e32 v144, v77, v119
	v_fmac_f32_e32 v145, v77, v120
	v_fmac_f32_e32 v146, v77, v121
	v_fmac_f32_e32 v46, v78, v115
	v_fmac_f32_e32 v140, v78, v116
	v_fmac_f32_e32 v141, v78, v117
	v_fmac_f32_e32 v142, v78, v118
	v_fmac_f32_e32 v143, v78, v119
	v_fmac_f32_e32 v144, v78, v120
	v_fmac_f32_e32 v145, v78, v121
	s_waitcnt lgkmcnt(5)
	v_fmac_f32_e32 v146, v78, v122
	v_fmac_f32_e32 v46, v79, v116
	v_fmac_f32_e32 v140, v79, v117
	v_fmac_f32_e32 v141, v79, v118
	v_fmac_f32_e32 v142, v79, v119
	v_fmac_f32_e32 v143, v79, v120
	v_fmac_f32_e32 v144, v79, v121
	v_fmac_f32_e32 v145, v79, v122
	v_fmac_f32_e32 v146, v79, v123
	v_fmac_f32_e32 v46, v80, v117
	v_fmac_f32_e32 v140, v80, v118
	v_fmac_f32_e32 v141, v80, v119
	v_fmac_f32_e32 v142, v80, v120
	v_fmac_f32_e32 v143, v80, v121
	v_fmac_f32_e32 v144, v80, v122
	v_fmac_f32_e32 v145, v80, v123
	s_waitcnt lgkmcnt(4)
	v_fmac_f32_e32 v146, v80, v124
	v_fmac_f32_e32 v46, v81, v118
	v_fmac_f32_e32 v140, v81, v119
	v_fmac_f32_e32 v141, v81, v120
	v_fmac_f32_e32 v142, v81, v121
	v_fmac_f32_e32 v143, v81, v122
	v_fmac_f32_e32 v144, v81, v123
	v_fmac_f32_e32 v145, v81, v124
	v_fmac_f32_e32 v146, v81, v125
	v_fmac_f32_e32 v46, v82, v119
	v_fmac_f32_e32 v140, v82, v120
	v_fmac_f32_e32 v141, v82, v121
	v_fmac_f32_e32 v142, v82, v122
	v_fmac_f32_e32 v143, v82, v123
	v_fmac_f32_e32 v144, v82, v124
	v_fmac_f32_e32 v145, v82, v125
	s_waitcnt lgkmcnt(3)
	v_fmac_f32_e32 v146, v82, v126
	v_fmac_f32_e32 v46, v83, v120
	v_fmac_f32_e32 v140, v83, v121
	v_fmac_f32_e32 v141, v83, v122
	v_fmac_f32_e32 v142, v83, v123
	v_fmac_f32_e32 v143, v83, v124
	v_fmac_f32_e32 v144, v83, v125
	v_fmac_f32_e32 v145, v83, v126
	v_fmac_f32_e32 v146, v83, v127
	v_fmac_f32_e32 v46, v84, v121
	v_fmac_f32_e32 v140, v84, v122
	v_fmac_f32_e32 v141, v84, v123
	v_fmac_f32_e32 v142, v84, v124
	v_fmac_f32_e32 v143, v84, v125
	v_fmac_f32_e32 v144, v84, v126
	v_fmac_f32_e32 v145, v84, v127
	s_waitcnt lgkmcnt(2)
	v_fmac_f32_e32 v146, v84, v128
	v_fmac_f32_e32 v46, v85, v122
	v_fmac_f32_e32 v140, v85, v123
	v_fmac_f32_e32 v141, v85, v124
	v_fmac_f32_e32 v142, v85, v125
	v_fmac_f32_e32 v143, v85, v126
	v_fmac_f32_e32 v144, v85, v127
	v_fmac_f32_e32 v145, v85, v128
	v_fmac_f32_e32 v146, v85, v129
	v_fmac_f32_e32 v46, v86, v123
	v_fmac_f32_e32 v140, v86, v124
	v_fmac_f32_e32 v141, v86, v125
	v_fmac_f32_e32 v142, v86, v126
	v_fmac_f32_e32 v143, v86, v127
	v_fmac_f32_e32 v144, v86, v128
	v_fmac_f32_e32 v145, v86, v129
	s_waitcnt lgkmcnt(1)
	v_fmac_f32_e32 v146, v86, v130
	v_fmac_f32_e32 v46, v87, v124
	v_fmac_f32_e32 v140, v87, v125
	v_fmac_f32_e32 v141, v87, v126
	v_fmac_f32_e32 v142, v87, v127
	v_fmac_f32_e32 v143, v87, v128
	v_fmac_f32_e32 v144, v87, v129
	v_fmac_f32_e32 v145, v87, v130
	v_fmac_f32_e32 v146, v87, v131
	v_fmac_f32_e32 v46, v88, v125
	v_fmac_f32_e32 v140, v88, v126
	s_mov_b32 s2, 8
	s_mov_b64 s[10:11], 0
	s_and_b64 vcc, exec, vcc
	v_fmac_f32_e32 v141, v88, v127
	v_fmac_f32_e32 v142, v88, v128
	v_fmac_f32_e32 v143, v88, v129
	v_fmac_f32_e32 v144, v88, v130
	v_fmac_f32_e32 v145, v88, v131
	s_waitcnt lgkmcnt(0)
	v_fmac_f32_e32 v146, v88, v132
	v_fmac_f32_e32 v46, v89, v126
	v_fmac_f32_e32 v140, v89, v127
	v_add_u32_e32 v134, 0x800, v103
	v_add_u32_e32 v135, 0xc00, v103
	v_add_u32_e32 v136, 0x1000, v103
	v_add_u32_e32 v137, 0x1400, v103
	v_add_u32_e32 v138, 0x1800, v103
	v_add_u32_e32 v139, 0x1c00, v103
	v_fmac_f32_e32 v141, v89, v128
	v_fmac_f32_e32 v142, v89, v129
	v_fmac_f32_e32 v143, v89, v130
	v_fmac_f32_e32 v144, v89, v131
	v_fmac_f32_e32 v145, v89, v132
	v_fmac_f32_e32 v146, v89, v133
	ds_write2st64_b32 v103, v46, v140 offset0:248 offset1:252
	ds_write_b32 v134, v141 offset:63488
	ds_write_b32 v135, v142 offset:63488
	ds_write_b32 v136, v143 offset:63488
	ds_write_b32 v137, v144 offset:63488
	ds_write_b32 v138, v145 offset:63488
	ds_write_b32 v139, v146 offset:63488
	s_cbranch_vccz .LBB0_696
	v_add_u32_e32 v46, s17, v93
	s_waitcnt lgkmcnt(0)
	s_barrier
	ds_read_b128 v[46:49], v46 offset:63488
	s_waitcnt lgkmcnt(0)
	v_mov_b32_e32 v50, v47
	v_mov_b32_e32 v51, v48
	v_mov_b32_e32 v52, v46
	v_mov_b32_e32 v53, v49
	v_pk_add_f32 v[50:51], v[50:51], v[52:53]
	s_nop 0
	v_add_f32_e32 v50, v50, v51
	s_nop 1
	v_add_f32_dpp v50, v50, v50 quad_perm:[1,0,3,2] row_mask:0xf bank_mask:0xf
	s_nop 1
	v_add_f32_dpp v50, v50, v50 quad_perm:[2,3,0,1] row_mask:0xf bank_mask:0xf
	s_nop 1
	v_add_f32_dpp v50, v50, v50 row_half_mirror row_mask:0xf bank_mask:0xf
	s_nop 1
	v_add_f32_dpp v50, v50, v50 row_mirror row_mask:0xf bank_mask:0xf
	v_mov_b32_e32 v51, v50
	s_nop 1
	v_permlane16_swap_b32 v50, v51
	s_nop 1
	v_add_f32_e32 v50, v50, v51
	v_mov_b32_e32 v51, v50
	s_nop 1
	v_permlane32_swap_b32 v50, v51
	s_nop 1
	v_add_f32_e32 v50, v50, v51
	v_fmamk_f32 v47, v50, 0xbb800000, v47
	v_fmamk_f32 v46, v50, 0xbb800000, v46
	v_fmamk_f32 v49, v50, 0xbb800000, v49
	v_fmac_f32_e32 v48, 0xbb800000, v50
	v_pk_mul_f32 v[50:51], v[48:49], v[48:49]
	v_pk_mul_f32 v[52:53], v[46:47], v[46:47]
	s_nop 0
	v_pk_mov_b32 v[104:105], v[52:53], v[50:51] op_sel:[1,0]
	v_mov_b32_e32 v53, v51
	v_pk_add_f32 v[50:51], v[104:105], v[52:53]
	s_nop 0
	v_add_f32_e32 v50, v50, v51
	s_nop 1
	v_add_f32_dpp v50, v50, v50 quad_perm:[1,0,3,2] row_mask:0xf bank_mask:0xf
	s_nop 1
	v_add_f32_dpp v50, v50, v50 quad_perm:[2,3,0,1] row_mask:0xf bank_mask:0xf
	s_nop 1
	v_add_f32_dpp v50, v50, v50 row_half_mirror row_mask:0xf bank_mask:0xf
	s_nop 1
	v_add_f32_dpp v50, v50, v50 row_mirror row_mask:0xf bank_mask:0xf
	v_mov_b32_e32 v51, v50
	s_nop 1
	v_permlane16_swap_b32 v50, v51
	s_nop 1
	v_add_f32_e32 v50, v50, v51
	v_mov_b32_e32 v51, v50
	s_nop 1
	v_permlane32_swap_b32 v50, v51
	s_nop 1
	v_add_f32_e32 v50, v50, v51
	v_fmamk_f32 v50, v50, 0x3b800000, v247
	v_cmp_gt_f32_e32 vcc, s12, v50
	v_mul_f32_e32 v51, 0x4f800000, v50
	s_nop 0
	v_cndmask_b32_e32 v50, v50, v51, vcc
	v_sqrt_f32_e32 v51, v50
	s_nop 0
	v_add_u32_e32 v52, -1, v51
	v_fma_f32 v53, -v52, v51, v50
	v_cmp_ge_f32_e64 s[10:11], 0, v53
	v_add_u32_e32 v53, 1, v51
	s_nop 0
	v_cndmask_b32_e64 v52, v51, v52, s[10:11]
	v_fma_f32 v51, -v53, v51, v50
	v_cmp_lt_f32_e64 s[10:11], 0, v51
	s_nop 1
	v_cndmask_b32_e64 v51, v52, v53, s[10:11]
	v_mul_f32_e32 v52, 0x37800000, v51
	v_cndmask_b32_e32 v51, v51, v52, vcc
	v_cmp_class_f32_e32 vcc, v50, v246
	s_nop 1
	v_cndmask_b32_e32 v50, v51, v50, vcc
	v_div_scale_f32 v51, s[2:3], v50, v50, 1.0
	v_rcp_f32_e32 v52, v51
	s_add_i32 s2, s24, s16
	s_ashr_i32 s3, s2, 31
	s_lshl_b64 s[2:3], s[2:3], 11
	v_fma_f32 v53, -v51, v52, 1.0
	v_fmac_f32_e32 v52, v53, v52
	v_div_scale_f32 v53, vcc, 1.0, v50, 1.0
	v_mul_f32_e32 v103, v53, v52
	v_fma_f32 v104, -v51, v103, v53
	v_fmac_f32_e32 v103, v104, v52
	v_fma_f32 v51, -v51, v103, v53
	v_div_fmas_f32 v51, v51, v52, v103
	v_div_fixup_f32 v50, v51, v50, 1.0
	v_pk_mul_f32 v[46:47], v[46:47], v[50:51] op_sel_hi:[1,0]
	v_pk_mul_f32 v[48:49], v[48:49], v[50:51] op_sel_hi:[1,0]
	v_pk_fma_f32 v[46:47], v[38:39], v[46:47], v[42:43]
	v_pk_fma_f32 v[48:49], v[40:41], v[48:49], v[44:45]
	v_mul_f32_e32 v50, 0xbfb8aa3b, v46
	v_mul_f32_e32 v51, 0xbfb8aa3b, v47
	v_exp_f32_e32 v50, v50
	v_exp_f32_e32 v51, v51
	v_add_f32_e32 v50, 1.0, v50
	v_add_f32_e32 v51, 1.0, v51
	v_rcp_f32_e32 v50, v50
	v_rcp_f32_e32 v51, v51
	s_nop 0
	v_pk_mul_f32 v[46:47], v[46:47], v[50:51]
	v_mul_f32_e32 v50, 0xbfb8aa3b, v48
	v_mul_f32_e32 v51, 0xbfb8aa3b, v49
	v_exp_f32_e32 v50, v50
	v_exp_f32_e32 v51, v51
	v_cvt_pk_bf16_f32 v46, v46, v47
	v_add_f32_e32 v50, 1.0, v50
	v_add_f32_e32 v51, 1.0, v51
	v_rcp_f32_e32 v50, v50
	v_rcp_f32_e32 v51, v51
	s_nop 0
	v_pk_mul_f32 v[48:49], v[48:49], v[50:51]
	s_nop 0
	v_cvt_pk_bf16_f32 v47, v48, v49
	v_lshl_add_u64 v[48:49], v[54:55], 0, s[2:3]
	global_store_dwordx2 v[48:49], v[46:47], off offset:1536
	v_add_u32_e32 v46, s19, v93
	ds_read_b128 v[46:49], v46 offset:63488
	s_waitcnt lgkmcnt(0)
	v_mov_b32_e32 v50, v47
	v_mov_b32_e32 v51, v48
	v_mov_b32_e32 v52, v46
	v_mov_b32_e32 v53, v49
	v_pk_add_f32 v[50:51], v[50:51], v[52:53]
	s_nop 0
	v_add_f32_e32 v50, v50, v51
	s_nop 1
	v_add_f32_dpp v50, v50, v50 quad_perm:[1,0,3,2] row_mask:0xf bank_mask:0xf
	s_nop 1
	v_add_f32_dpp v50, v50, v50 quad_perm:[2,3,0,1] row_mask:0xf bank_mask:0xf
	s_nop 1
	v_add_f32_dpp v50, v50, v50 row_half_mirror row_mask:0xf bank_mask:0xf
	s_nop 1
	v_add_f32_dpp v50, v50, v50 row_mirror row_mask:0xf bank_mask:0xf
	v_mov_b32_e32 v51, v50
	s_nop 1
	v_permlane16_swap_b32 v50, v51
	s_nop 1
	v_add_f32_e32 v50, v50, v51
	v_mov_b32_e32 v51, v50
	s_nop 1
	v_permlane32_swap_b32 v50, v51
	s_nop 1
	v_add_f32_e32 v50, v50, v51
	v_fmamk_f32 v47, v50, 0xbb800000, v47
	v_fmamk_f32 v46, v50, 0xbb800000, v46
	v_fmamk_f32 v49, v50, 0xbb800000, v49
	v_fmac_f32_e32 v48, 0xbb800000, v50
	v_pk_mul_f32 v[50:51], v[48:49], v[48:49]
	v_pk_mul_f32 v[52:53], v[46:47], v[46:47]
	s_nop 0
	v_pk_mov_b32 v[104:105], v[52:53], v[50:51] op_sel:[1,0]
	v_mov_b32_e32 v53, v51
	v_pk_add_f32 v[50:51], v[104:105], v[52:53]
	s_nop 0
	v_add_f32_e32 v50, v50, v51
	s_nop 1
	v_add_f32_dpp v50, v50, v50 quad_perm:[1,0,3,2] row_mask:0xf bank_mask:0xf
	s_nop 1
	v_add_f32_dpp v50, v50, v50 quad_perm:[2,3,0,1] row_mask:0xf bank_mask:0xf
	s_nop 1
	v_add_f32_dpp v50, v50, v50 row_half_mirror row_mask:0xf bank_mask:0xf
	s_nop 1
	v_add_f32_dpp v50, v50, v50 row_mirror row_mask:0xf bank_mask:0xf
	v_mov_b32_e32 v51, v50
	s_nop 1
	v_permlane16_swap_b32 v50, v51
	s_nop 1
	v_add_f32_e32 v50, v50, v51
	v_mov_b32_e32 v51, v50
	s_nop 1
	v_permlane32_swap_b32 v50, v51
	s_nop 1
	v_add_f32_e32 v50, v50, v51
	v_fmamk_f32 v50, v50, 0x3b800000, v247
	v_cmp_gt_f32_e32 vcc, s12, v50
	v_mul_f32_e32 v51, 0x4f800000, v50
	s_nop 0
	v_cndmask_b32_e32 v50, v50, v51, vcc
	v_sqrt_f32_e32 v51, v50
	s_nop 0
	v_add_u32_e32 v52, -1, v51
	v_fma_f32 v53, -v52, v51, v50
	v_cmp_ge_f32_e64 s[10:11], 0, v53
	v_add_u32_e32 v53, 1, v51
	s_nop 0
	v_cndmask_b32_e64 v52, v51, v52, s[10:11]
	v_fma_f32 v51, -v53, v51, v50
	v_cmp_lt_f32_e64 s[10:11], 0, v51
	s_nop 1
	v_cndmask_b32_e64 v51, v52, v53, s[10:11]
	v_mul_f32_e32 v52, 0x37800000, v51
	v_cndmask_b32_e32 v51, v51, v52, vcc
	v_cmp_class_f32_e32 vcc, v50, v246
	s_nop 1
	v_cndmask_b32_e32 v50, v51, v50, vcc
	v_div_scale_f32 v51, s[2:3], v50, v50, 1.0
	v_rcp_f32_e32 v52, v51
	s_add_i32 s2, s24, s18
	s_ashr_i32 s3, s2, 31
	s_lshl_b64 s[2:3], s[2:3], 11
	v_fma_f32 v53, -v51, v52, 1.0
	v_fmac_f32_e32 v52, v53, v52
	v_div_scale_f32 v53, vcc, 1.0, v50, 1.0
	v_mul_f32_e32 v103, v53, v52
	v_fma_f32 v104, -v51, v103, v53
	v_fmac_f32_e32 v103, v104, v52
	v_fma_f32 v51, -v51, v103, v53
	v_div_fmas_f32 v51, v51, v52, v103
	v_div_fixup_f32 v50, v51, v50, 1.0
	v_pk_mul_f32 v[46:47], v[46:47], v[50:51] op_sel_hi:[1,0]
	v_pk_mul_f32 v[48:49], v[48:49], v[50:51] op_sel_hi:[1,0]
	v_pk_fma_f32 v[46:47], v[38:39], v[46:47], v[42:43]
	v_pk_fma_f32 v[48:49], v[40:41], v[48:49], v[44:45]
	v_mul_f32_e32 v50, 0xbfb8aa3b, v46
	v_mul_f32_e32 v51, 0xbfb8aa3b, v47
	v_exp_f32_e32 v50, v50
	v_exp_f32_e32 v51, v51
	v_add_f32_e32 v50, 1.0, v50
	v_add_f32_e32 v51, 1.0, v51
	v_rcp_f32_e32 v50, v50
	v_rcp_f32_e32 v51, v51
	s_nop 0
	v_pk_mul_f32 v[46:47], v[46:47], v[50:51]
	v_mul_f32_e32 v50, 0xbfb8aa3b, v48
	v_mul_f32_e32 v51, 0xbfb8aa3b, v49
	v_exp_f32_e32 v50, v50
	v_exp_f32_e32 v51, v51
	v_cvt_pk_bf16_f32 v46, v46, v47
	v_add_f32_e32 v50, 1.0, v50
	v_add_f32_e32 v51, 1.0, v51
	v_rcp_f32_e32 v50, v50
	v_rcp_f32_e32 v51, v51
	s_nop 0
	v_pk_mul_f32 v[48:49], v[48:49], v[50:51]
	s_nop 0
	v_cvt_pk_bf16_f32 v47, v48, v49
	v_lshl_add_u64 v[48:49], v[54:55], 0, s[2:3]
	global_store_dwordx2 v[48:49], v[46:47], off offset:1536
	v_add_u32_e32 v46, s21, v93
	ds_read_b128 v[46:49], v46 offset:63488
	s_waitcnt lgkmcnt(0)
	v_mov_b32_e32 v50, v47
	v_mov_b32_e32 v51, v48
	v_mov_b32_e32 v52, v46
	v_mov_b32_e32 v53, v49
	v_pk_add_f32 v[50:51], v[50:51], v[52:53]
	s_nop 0
	v_add_f32_e32 v50, v50, v51
	s_nop 1
	v_add_f32_dpp v50, v50, v50 quad_perm:[1,0,3,2] row_mask:0xf bank_mask:0xf
	s_nop 1
	v_add_f32_dpp v50, v50, v50 quad_perm:[2,3,0,1] row_mask:0xf bank_mask:0xf
	s_nop 1
	v_add_f32_dpp v50, v50, v50 row_half_mirror row_mask:0xf bank_mask:0xf
	s_nop 1
	v_add_f32_dpp v50, v50, v50 row_mirror row_mask:0xf bank_mask:0xf
	v_mov_b32_e32 v51, v50
	s_nop 1
	v_permlane16_swap_b32 v50, v51
	s_nop 1
	v_add_f32_e32 v50, v50, v51
	v_mov_b32_e32 v51, v50
	s_nop 1
	v_permlane32_swap_b32 v50, v51
	s_nop 1
	v_add_f32_e32 v50, v50, v51
	v_fmamk_f32 v47, v50, 0xbb800000, v47
	v_fmamk_f32 v46, v50, 0xbb800000, v46
	v_fmamk_f32 v49, v50, 0xbb800000, v49
	v_fmac_f32_e32 v48, 0xbb800000, v50
	v_pk_mul_f32 v[50:51], v[48:49], v[48:49]
	v_pk_mul_f32 v[52:53], v[46:47], v[46:47]
	s_nop 0
	v_pk_mov_b32 v[104:105], v[52:53], v[50:51] op_sel:[1,0]
	v_mov_b32_e32 v53, v51
	v_pk_add_f32 v[50:51], v[104:105], v[52:53]
	s_nop 0
	v_add_f32_e32 v50, v50, v51
	s_nop 1
	v_add_f32_dpp v50, v50, v50 quad_perm:[1,0,3,2] row_mask:0xf bank_mask:0xf
	s_nop 1
	v_add_f32_dpp v50, v50, v50 quad_perm:[2,3,0,1] row_mask:0xf bank_mask:0xf
	s_nop 1
	v_add_f32_dpp v50, v50, v50 row_half_mirror row_mask:0xf bank_mask:0xf
	s_nop 1
	v_add_f32_dpp v50, v50, v50 row_mirror row_mask:0xf bank_mask:0xf
	v_mov_b32_e32 v51, v50
	s_nop 1
	v_permlane16_swap_b32 v50, v51
	s_nop 1
	v_add_f32_e32 v50, v50, v51
	v_mov_b32_e32 v51, v50
	s_nop 1
	v_permlane32_swap_b32 v50, v51
	s_nop 1
	v_add_f32_e32 v50, v50, v51
	v_fmamk_f32 v50, v50, 0x3b800000, v247
	v_cmp_gt_f32_e32 vcc, s12, v50
	v_mul_f32_e32 v51, 0x4f800000, v50
	s_nop 0
	v_cndmask_b32_e32 v50, v50, v51, vcc
	v_sqrt_f32_e32 v51, v50
	s_nop 0
	v_add_u32_e32 v52, -1, v51
	v_fma_f32 v53, -v52, v51, v50
	v_cmp_ge_f32_e64 s[10:11], 0, v53
	v_add_u32_e32 v53, 1, v51
	s_nop 0
	v_cndmask_b32_e64 v52, v51, v52, s[10:11]
	v_fma_f32 v51, -v53, v51, v50
	v_cmp_lt_f32_e64 s[10:11], 0, v51
	s_nop 1
	v_cndmask_b32_e64 v51, v52, v53, s[10:11]
	v_mul_f32_e32 v52, 0x37800000, v51
	v_cndmask_b32_e32 v51, v51, v52, vcc
	v_cmp_class_f32_e32 vcc, v50, v246
	s_nop 1
	v_cndmask_b32_e32 v50, v51, v50, vcc
	v_div_scale_f32 v51, s[2:3], v50, v50, 1.0
	v_rcp_f32_e32 v52, v51
	s_add_i32 s2, s24, s20
	s_ashr_i32 s3, s2, 31
	s_lshl_b64 s[2:3], s[2:3], 11
	v_fma_f32 v53, -v51, v52, 1.0
	v_fmac_f32_e32 v52, v53, v52
	v_div_scale_f32 v53, vcc, 1.0, v50, 1.0
	v_mul_f32_e32 v103, v53, v52
	v_fma_f32 v104, -v51, v103, v53
	v_fmac_f32_e32 v103, v104, v52
	v_fma_f32 v51, -v51, v103, v53
	v_div_fmas_f32 v51, v51, v52, v103
	v_div_fixup_f32 v50, v51, v50, 1.0
	v_pk_mul_f32 v[46:47], v[46:47], v[50:51] op_sel_hi:[1,0]
	v_pk_mul_f32 v[48:49], v[48:49], v[50:51] op_sel_hi:[1,0]
	v_pk_fma_f32 v[46:47], v[38:39], v[46:47], v[42:43]
	v_pk_fma_f32 v[48:49], v[40:41], v[48:49], v[44:45]
	v_mul_f32_e32 v50, 0xbfb8aa3b, v46
	v_mul_f32_e32 v51, 0xbfb8aa3b, v47
	v_exp_f32_e32 v50, v50
	v_exp_f32_e32 v51, v51
	v_add_f32_e32 v50, 1.0, v50
	v_add_f32_e32 v51, 1.0, v51
	v_rcp_f32_e32 v50, v50
	v_rcp_f32_e32 v51, v51
	s_nop 0
	v_pk_mul_f32 v[46:47], v[46:47], v[50:51]
	v_mul_f32_e32 v50, 0xbfb8aa3b, v48
	v_mul_f32_e32 v51, 0xbfb8aa3b, v49
	v_exp_f32_e32 v50, v50
	v_exp_f32_e32 v51, v51
	v_cvt_pk_bf16_f32 v46, v46, v47
	v_add_f32_e32 v50, 1.0, v50
	v_add_f32_e32 v51, 1.0, v51
	v_rcp_f32_e32 v50, v50
	v_rcp_f32_e32 v51, v51
	s_nop 0
	v_pk_mul_f32 v[48:49], v[48:49], v[50:51]
	s_nop 0
	v_cvt_pk_bf16_f32 v47, v48, v49
	v_lshl_add_u64 v[48:49], v[54:55], 0, s[2:3]
	global_store_dwordx2 v[48:49], v[46:47], off offset:1536
	v_add_u32_e32 v46, s23, v93
	ds_read_b128 v[46:49], v46 offset:63488
	s_waitcnt lgkmcnt(0)
	v_mov_b32_e32 v50, v47
	v_mov_b32_e32 v51, v48
	v_mov_b32_e32 v52, v46
	v_mov_b32_e32 v53, v49
	v_pk_add_f32 v[50:51], v[50:51], v[52:53]
	s_nop 0
	v_add_f32_e32 v50, v50, v51
	s_nop 1
	v_add_f32_dpp v50, v50, v50 quad_perm:[1,0,3,2] row_mask:0xf bank_mask:0xf
	s_nop 1
	v_add_f32_dpp v50, v50, v50 quad_perm:[2,3,0,1] row_mask:0xf bank_mask:0xf
	s_nop 1
	v_add_f32_dpp v50, v50, v50 row_half_mirror row_mask:0xf bank_mask:0xf
	s_nop 1
	v_add_f32_dpp v50, v50, v50 row_mirror row_mask:0xf bank_mask:0xf
	v_mov_b32_e32 v51, v50
	s_nop 1
	v_permlane16_swap_b32 v50, v51
	s_nop 1
	v_add_f32_e32 v50, v50, v51
	v_mov_b32_e32 v51, v50
	s_nop 1
	v_permlane32_swap_b32 v50, v51
	s_nop 1
	v_add_f32_e32 v50, v50, v51
	v_fmamk_f32 v47, v50, 0xbb800000, v47
	v_fmamk_f32 v46, v50, 0xbb800000, v46
	v_fmamk_f32 v49, v50, 0xbb800000, v49
	v_fmac_f32_e32 v48, 0xbb800000, v50
	v_pk_mul_f32 v[50:51], v[48:49], v[48:49]
	v_pk_mul_f32 v[52:53], v[46:47], v[46:47]
	s_nop 0
	v_pk_mov_b32 v[104:105], v[52:53], v[50:51] op_sel:[1,0]
	v_mov_b32_e32 v53, v51
	v_pk_add_f32 v[50:51], v[104:105], v[52:53]
	s_nop 0
	v_add_f32_e32 v50, v50, v51
	s_nop 1
	v_add_f32_dpp v50, v50, v50 quad_perm:[1,0,3,2] row_mask:0xf bank_mask:0xf
	s_nop 1
	v_add_f32_dpp v50, v50, v50 quad_perm:[2,3,0,1] row_mask:0xf bank_mask:0xf
	s_nop 1
	v_add_f32_dpp v50, v50, v50 row_half_mirror row_mask:0xf bank_mask:0xf
	s_nop 1
	v_add_f32_dpp v50, v50, v50 row_mirror row_mask:0xf bank_mask:0xf
	v_mov_b32_e32 v51, v50
	s_nop 1
	v_permlane16_swap_b32 v50, v51
	s_nop 1
	v_add_f32_e32 v50, v50, v51
	v_mov_b32_e32 v51, v50
	s_nop 1
	v_permlane32_swap_b32 v50, v51
	s_nop 1
	v_add_f32_e32 v50, v50, v51
	v_fmamk_f32 v50, v50, 0x3b800000, v247
	v_cmp_gt_f32_e32 vcc, s12, v50
	v_mul_f32_e32 v51, 0x4f800000, v50
	s_nop 0
	v_cndmask_b32_e32 v50, v50, v51, vcc
	v_sqrt_f32_e32 v51, v50
	s_nop 0
	v_add_u32_e32 v52, -1, v51
	v_fma_f32 v53, -v52, v51, v50
	v_cmp_ge_f32_e64 s[10:11], 0, v53
	v_add_u32_e32 v53, 1, v51
	s_nop 0
	v_cndmask_b32_e64 v52, v51, v52, s[10:11]
	v_fma_f32 v51, -v53, v51, v50
	v_cmp_lt_f32_e64 s[10:11], 0, v51
	s_nop 1
	v_cndmask_b32_e64 v51, v52, v53, s[10:11]
	v_mul_f32_e32 v52, 0x37800000, v51
	v_cndmask_b32_e32 v51, v51, v52, vcc
	v_cmp_class_f32_e32 vcc, v50, v246
	s_nop 1
	v_cndmask_b32_e32 v50, v51, v50, vcc
	v_div_scale_f32 v51, s[2:3], v50, v50, 1.0
	v_rcp_f32_e32 v52, v51
	s_add_i32 s2, s24, s22
	s_ashr_i32 s3, s2, 31
	s_lshl_b64 s[2:3], s[2:3], 11
	v_fma_f32 v53, -v51, v52, 1.0
	v_fmac_f32_e32 v52, v53, v52
	v_div_scale_f32 v53, vcc, 1.0, v50, 1.0
	v_mul_f32_e32 v103, v53, v52
	v_fma_f32 v104, -v51, v103, v53
	v_fmac_f32_e32 v103, v104, v52
	v_fma_f32 v51, -v51, v103, v53
	v_div_fmas_f32 v51, v51, v52, v103
	v_div_fixup_f32 v50, v51, v50, 1.0
	v_pk_mul_f32 v[46:47], v[46:47], v[50:51] op_sel_hi:[1,0]
	v_pk_mul_f32 v[48:49], v[48:49], v[50:51] op_sel_hi:[1,0]
	v_pk_fma_f32 v[46:47], v[38:39], v[46:47], v[42:43]
	v_pk_fma_f32 v[48:49], v[40:41], v[48:49], v[44:45]
	v_mul_f32_e32 v50, 0xbfb8aa3b, v46
	v_mul_f32_e32 v51, 0xbfb8aa3b, v47
	v_exp_f32_e32 v50, v50
	v_exp_f32_e32 v51, v51
	s_cmp_eq_u32 s15, s77
	v_add_f32_e32 v50, 1.0, v50
	v_add_f32_e32 v51, 1.0, v51
	v_rcp_f32_e32 v50, v50
	v_rcp_f32_e32 v51, v51
	s_nop 0
	v_pk_mul_f32 v[46:47], v[46:47], v[50:51]
	v_mul_f32_e32 v50, 0xbfb8aa3b, v48
	v_mul_f32_e32 v51, 0xbfb8aa3b, v49
	v_exp_f32_e32 v50, v50
	v_exp_f32_e32 v51, v51
	v_cvt_pk_bf16_f32 v46, v46, v47
	v_add_f32_e32 v50, 1.0, v50
	v_add_f32_e32 v51, 1.0, v51
	v_rcp_f32_e32 v50, v50
	v_rcp_f32_e32 v51, v51
	s_nop 0
	v_pk_mul_f32 v[48:49], v[48:49], v[50:51]
	s_nop 0
	v_cvt_pk_bf16_f32 v47, v48, v49
	v_lshl_add_u64 v[48:49], v[54:55], 0, s[2:3]
	global_store_dwordx2 v[48:49], v[46:47], off offset:1536
	s_barrier
	s_cbranch_scc0 .LBB0_677
	s_mov_b64 s[0:1], 0
